# adds: prologue row_to_bf16 issues its 8 loads per row together instead of load+wait ladder
# baseline (speedup 1.0000x reference)
.LBB0_1214:
	global_load_dwordx4 v[100:103], v[6:7], off offset:-4096 nt
	global_load_dwordx4 v[104:107], v[6:7], off offset:-3072 nt
	global_load_dwordx4 v[108:111], v[6:7], off offset:-2048 nt
	global_load_dwordx4 v[112:115], v[6:7], off offset:-1024 nt
	global_load_dwordx4 v[116:119], v[6:7], off nt
	global_load_dwordx4 v[120:123], v[6:7], off offset:1024 nt
	global_load_dwordx4 v[124:127], v[6:7], off offset:2048 nt
	global_load_dwordx4 v[128:131], v[6:7], off offset:3072 nt
	s_waitcnt vmcnt(0)
	v_mov_b64_e32 v[10:11], v[100:101]
	v_mov_b64_e32 v[12:13], v[102:103]
	v_lshl_add_u64 v[18:19], s[72:73], 0, v[8:9]
	s_mov_b32 s0, 0x1000000
	v_cvt_pk_bf16_f32 v20, v10, v11
	v_cvt_pk_bf16_f32 v21, v12, v13
	v_mul_f32_e32 v3, v11, v11
	v_fmac_f32_e32 v3, v10, v10
	v_add_co_u32_e64 v10, s[0:1], s0, v18
	v_mul_f32_e32 v14, v13, v13
	s_nop 0
	v_addc_co_u32_e64 v11, s[0:1], 0, v19, s[0:1]
	global_store_dwordx2 v[10:11], v[20:21], off
	v_mov_b64_e32 v[18:19], v[104:105]
	v_mov_b64_e32 v[20:21], v[106:107]
	v_fmac_f32_e32 v14, v12, v12
	v_add_f32_e32 v3, v3, v14
	v_mul_f32_e32 v12, v19, v19
	v_mul_f32_e32 v13, v21, v21
	v_fmac_f32_e32 v12, v18, v18
	v_fmac_f32_e32 v13, v20, v20
	v_add_f32_e32 v12, v12, v13
	v_add_f32_e32 v3, v3, v12
	v_cvt_pk_bf16_f32 v12, v18, v19
	v_cvt_pk_bf16_f32 v13, v20, v21
	global_store_dwordx2 v[10:11], v[12:13], off offset:512
	v_mov_b64_e32 v[18:19], v[108:109]
	v_mov_b64_e32 v[20:21], v[110:111]
	v_mul_f32_e32 v12, v19, v19
	v_mul_f32_e32 v13, v21, v21
	v_fmac_f32_e32 v12, v18, v18
	v_fmac_f32_e32 v13, v20, v20
	v_add_f32_e32 v12, v12, v13
	v_add_f32_e32 v3, v3, v12
	v_cvt_pk_bf16_f32 v12, v18, v19
	v_cvt_pk_bf16_f32 v13, v20, v21
	global_store_dwordx2 v[10:11], v[12:13], off offset:1024
	v_mov_b64_e32 v[18:19], v[112:113]
	v_mov_b64_e32 v[20:21], v[114:115]
	v_mul_f32_e32 v12, v19, v19
	v_mul_f32_e32 v13, v21, v21
	v_fmac_f32_e32 v12, v18, v18
	v_fmac_f32_e32 v13, v20, v20
	v_add_f32_e32 v12, v12, v13
	v_add_f32_e32 v3, v3, v12
	v_cvt_pk_bf16_f32 v12, v18, v19
	v_cvt_pk_bf16_f32 v13, v20, v21
	global_store_dwordx2 v[10:11], v[12:13], off offset:1536
	v_mov_b64_e32 v[18:19], v[116:117]
	v_mov_b64_e32 v[20:21], v[118:119]
	v_mul_f32_e32 v12, v19, v19
	v_mul_f32_e32 v13, v21, v21
	v_fmac_f32_e32 v12, v18, v18
	v_fmac_f32_e32 v13, v20, v20
	v_add_f32_e32 v12, v12, v13
	v_add_f32_e32 v3, v3, v12
	v_cvt_pk_bf16_f32 v12, v18, v19
	v_cvt_pk_bf16_f32 v13, v20, v21
	global_store_dwordx2 v[10:11], v[12:13], off offset:2048
	v_mov_b64_e32 v[18:19], v[120:121]
	v_mov_b64_e32 v[20:21], v[122:123]
	v_mul_f32_e32 v12, v19, v19
	v_mul_f32_e32 v13, v21, v21
	v_fmac_f32_e32 v12, v18, v18
	v_fmac_f32_e32 v13, v20, v20
	v_add_f32_e32 v12, v12, v13
	v_add_f32_e32 v3, v3, v12
	v_cvt_pk_bf16_f32 v12, v18, v19
	v_cvt_pk_bf16_f32 v13, v20, v21
	global_store_dwordx2 v[10:11], v[12:13], off offset:2560
	v_mov_b64_e32 v[18:19], v[124:125]
	v_mov_b64_e32 v[20:21], v[126:127]
	v_mul_f32_e32 v12, v19, v19
	v_mul_f32_e32 v13, v21, v21
	v_fmac_f32_e32 v12, v18, v18
	v_fmac_f32_e32 v13, v20, v20
	v_add_f32_e32 v12, v12, v13
	v_add_f32_e32 v3, v3, v12
	v_cvt_pk_bf16_f32 v12, v18, v19
	v_cvt_pk_bf16_f32 v13, v20, v21
	global_store_dwordx2 v[10:11], v[12:13], off offset:3072
	v_mov_b64_e32 v[18:19], v[128:129]
	v_mov_b64_e32 v[20:21], v[130:131]
	v_mul_f32_e32 v12, v19, v19
	v_mul_f32_e32 v13, v21, v21
	v_fmac_f32_e32 v12, v18, v18
	v_fmac_f32_e32 v13, v20, v20
	v_add_f32_e32 v12, v12, v13
	v_add_f32_e32 v3, v3, v12
	v_cvt_pk_bf16_f32 v12, v18, v19
	v_cvt_pk_bf16_f32 v13, v20, v21
	global_store_dwordx2 v[10:11], v[12:13], off offset:3584
	s_nop 0
	v_add_f32_dpp v3, v3, v3 quad_perm:[1,0,3,2] row_mask:0xf bank_mask:0xf bound_ctrl:1
	s_nop 1
	v_add_f32_dpp v3, v3, v3 quad_perm:[2,3,0,1] row_mask:0xf bank_mask:0xf bound_ctrl:1
	ds_swizzle_b32 v10, v3 offset:swizzle(SWAP,4)
	s_waitcnt lgkmcnt(0)
	v_add_f32_e32 v3, v3, v10
	ds_swizzle_b32 v10, v3 offset:swizzle(SWAP,8)
	s_waitcnt lgkmcnt(0)
	v_add_f32_e32 v3, v3, v10
	ds_swizzle_b32 v10, v3 offset:swizzle(SWAP,16)
	s_waitcnt lgkmcnt(0)
	v_add_f32_e32 v3, v3, v10
	v_mov_b32_e32 v10, v3
	s_nop 1
	v_permlane32_swap_b32_e32 v3, v10
	s_and_saveexec_b64 s[0:1], vcc
	s_cbranch_execz .LBB0_1213
	v_add_f32_e32 v3, v3, v10
	v_lshl_add_u64 v[12:13], s[72:73], 0, v[4:5]
	v_cndmask_b32_e64 v3, 0, v3, s[38:39]
	global_store_dword v[12:13], v3, off
	s_branch .LBB0_1213

.LBB0_1219:
	global_load_dwordx4 v[100:103], v[2:3], off offset:-4096 nt
	global_load_dwordx4 v[104:107], v[2:3], off offset:-3072 nt
	global_load_dwordx4 v[108:111], v[2:3], off offset:-2048 nt
	global_load_dwordx4 v[112:115], v[2:3], off offset:-1024 nt
	global_load_dwordx4 v[116:119], v[2:3], off nt
	global_load_dwordx4 v[120:123], v[2:3], off offset:1024 nt
	global_load_dwordx4 v[124:127], v[2:3], off offset:2048 nt
	global_load_dwordx4 v[128:131], v[2:3], off offset:3072 nt
	s_waitcnt vmcnt(0)
	v_mov_b64_e32 v[8:9], v[100:101]
	v_mov_b64_e32 v[10:11], v[102:103]
	v_lshl_add_u64 v[12:13], s[72:73], 0, v[6:7]
	s_mov_b32 s0, 0x300000
	v_mul_f32_e32 v0, v9, v9
	v_mul_f32_e32 v14, v11, v11
	v_fmac_f32_e32 v0, v8, v8
	v_fmac_f32_e32 v14, v10, v10
	v_add_f32_e32 v0, v0, v14
	v_cvt_pk_bf16_f32 v14, v8, v9
	v_add_co_u32_e64 v8, s[0:1], s0, v12
	v_cvt_pk_bf16_f32 v15, v10, v11
	s_nop 1
	v_addc_co_u32_e64 v9, s[0:1], 0, v13, s[0:1]
	global_store_dwordx2 v[8:9], v[14:15], off
	v_mov_b64_e32 v[10:11], v[104:105]
	v_mov_b64_e32 v[12:13], v[106:107]
	v_mul_f32_e32 v14, v11, v11
	v_fmac_f32_e32 v14, v10, v10
	v_mul_f32_e32 v15, v13, v13
	v_cvt_pk_bf16_f32 v10, v10, v11
	v_cvt_pk_bf16_f32 v11, v12, v13
	global_store_dwordx2 v[8:9], v[10:11], off offset:512
	v_fmac_f32_e32 v15, v12, v12
	v_mov_b64_e32 v[10:11], v[108:109]
	v_mov_b64_e32 v[12:13], v[110:111]
	v_add_f32_e32 v14, v14, v15
	v_add_f32_e32 v0, v0, v14
	v_mul_f32_e32 v14, v11, v11
	v_fmac_f32_e32 v14, v10, v10
	v_mul_f32_e32 v15, v13, v13
	v_cvt_pk_bf16_f32 v10, v10, v11
	v_cvt_pk_bf16_f32 v11, v12, v13
	global_store_dwordx2 v[8:9], v[10:11], off offset:1024
	v_fmac_f32_e32 v15, v12, v12
	v_mov_b64_e32 v[10:11], v[112:113]
	v_mov_b64_e32 v[12:13], v[114:115]
	v_add_f32_e32 v14, v14, v15
	v_add_f32_e32 v0, v0, v14
	v_mul_f32_e32 v14, v11, v11
	v_fmac_f32_e32 v14, v10, v10
	v_mul_f32_e32 v15, v13, v13
	v_cvt_pk_bf16_f32 v10, v10, v11
	v_cvt_pk_bf16_f32 v11, v12, v13
	global_store_dwordx2 v[8:9], v[10:11], off offset:1536
	v_fmac_f32_e32 v15, v12, v12
	v_mov_b64_e32 v[10:11], v[116:117]
	v_mov_b64_e32 v[12:13], v[118:119]
	v_add_f32_e32 v14, v14, v15
	v_add_f32_e32 v0, v0, v14
	v_mul_f32_e32 v14, v11, v11
	v_fmac_f32_e32 v14, v10, v10
	v_mul_f32_e32 v15, v13, v13
	v_cvt_pk_bf16_f32 v10, v10, v11
	v_cvt_pk_bf16_f32 v11, v12, v13
	global_store_dwordx2 v[8:9], v[10:11], off offset:2048
	v_fmac_f32_e32 v15, v12, v12
	v_mov_b64_e32 v[10:11], v[120:121]
	v_mov_b64_e32 v[12:13], v[122:123]
	v_add_f32_e32 v14, v14, v15
	v_add_f32_e32 v0, v0, v14
	v_mul_f32_e32 v14, v11, v11
	v_fmac_f32_e32 v14, v10, v10
	v_mul_f32_e32 v15, v13, v13
	v_cvt_pk_bf16_f32 v10, v10, v11
	v_cvt_pk_bf16_f32 v11, v12, v13
	global_store_dwordx2 v[8:9], v[10:11], off offset:2560
	v_fmac_f32_e32 v15, v12, v12
	v_mov_b64_e32 v[10:11], v[124:125]
	v_mov_b64_e32 v[12:13], v[126:127]
	v_add_f32_e32 v14, v14, v15
	v_add_f32_e32 v0, v0, v14
	v_mul_f32_e32 v14, v11, v11
	v_fmac_f32_e32 v14, v10, v10
	v_mul_f32_e32 v15, v13, v13
	v_cvt_pk_bf16_f32 v10, v10, v11
	v_cvt_pk_bf16_f32 v11, v12, v13
	global_store_dwordx2 v[8:9], v[10:11], off offset:3072
	v_fmac_f32_e32 v15, v12, v12
	v_mov_b64_e32 v[10:11], v[128:129]
	v_mov_b64_e32 v[12:13], v[130:131]
	v_add_f32_e32 v14, v14, v15
	v_add_f32_e32 v0, v0, v14
	v_mul_f32_e32 v14, v11, v11
	v_mul_f32_e32 v15, v13, v13
	v_fmac_f32_e32 v14, v10, v10
	v_fmac_f32_e32 v15, v12, v12
	v_add_f32_e32 v14, v14, v15
	v_add_f32_e32 v0, v0, v14
	v_cvt_pk_bf16_f32 v10, v10, v11
	v_cvt_pk_bf16_f32 v11, v12, v13
	global_store_dwordx2 v[8:9], v[10:11], off offset:3584
	s_nop 0
	v_add_f32_dpp v0, v0, v0 quad_perm:[1,0,3,2] row_mask:0xf bank_mask:0xf bound_ctrl:1
	s_nop 1
	v_add_f32_dpp v0, v0, v0 quad_perm:[2,3,0,1] row_mask:0xf bank_mask:0xf bound_ctrl:1
	ds_swizzle_b32 v8, v0 offset:swizzle(SWAP,4)
	s_waitcnt lgkmcnt(0)
	v_add_f32_e32 v0, v0, v8
	ds_swizzle_b32 v8, v0 offset:swizzle(SWAP,8)
	s_waitcnt lgkmcnt(0)
	v_add_f32_e32 v0, v0, v8
	ds_swizzle_b32 v8, v0 offset:swizzle(SWAP,16)
	s_waitcnt lgkmcnt(0)
	v_add_f32_e32 v0, v0, v8
	v_mov_b32_e32 v8, v0
	s_nop 1
	v_permlane32_swap_b32_e32 v0, v8
	s_and_saveexec_b64 s[0:1], vcc
	s_cbranch_execz .LBB0_1218
	v_add_f32_e32 v0, v0, v8
	v_lshl_add_u64 v[10:11], s[72:73], 0, v[4:5]
	v_cndmask_b32_e64 v0, 0, v0, s[38:39]
	global_store_dword v[10:11], v0, off
	s_branch .LBB0_1218
